# post_scan row pass: 16-lane reductions via DPP lane moves instead of ds_bpermute round trips
# speedup vs baseline: 1.0005x; 1.0005x over previous
; DI float lo16(unsigned u) { return __uint_as_float(u << 16); }
; DI float hi16(unsigned u) { return __uint_as_float(u & 0xffff0000u); }
; DI void post_scan(const PX& p, int l, int M, unsigned char* smem) {
;     ...
;   for (int r = wg; r < M; r += nw) {
;     const size_t ro = (size_t)r * 768 + lane * 12;
;     {
;       float x[12];
;       const uint2* hf = (const uint2*)(Hf + ro);
;       const uint2* hb = (const uint2*)(Hb + ro);
;       float s = 0.f;
; #pragma unroll
;       for (int i = 0; i < 3; i++) {
;         const uint2 a = hf[i], bq = hb[i];
;         x[4 * i] = lo16(a.x) + lo16(bq.x); x[4 * i + 1] = hi16(a.x) + hi16(bq.x);
;         x[4 * i + 2] = lo16(a.y) + lo16(bq.y); x[4 * i + 3] = hi16(a.y) + hi16(bq.y);
;         s += x[4 * i] + x[4 * i + 1] + x[4 * i + 2] + x[4 * i + 3];
;       }
; #pragma unroll
;       for (int o = 8; o >= 1; o >>= 1) s += __shfl_xor(s, o);
;       const float mu = s * (1.f / 192.f);
;       float q = 0.f;
; #pragma unroll
;       for (int i = 0; i < 12; i++) { x[i] -= mu; q += x[i] * x[i]; }
; #pragma unroll
;       for (int o = 8; o >= 1; o >>= 1) q += __shfl_xor(q, o);
;       const float rs = rsqrtf(q * (1.f / 192.f) + 1e-5f);
.LBB0_371:
	v_lshl_add_u64 v[30:31], v[28:29], 0, v[0:1]
	s_mov_b64 s[2:3], 0x2f618100
	v_add_co_u32_e32 v32, vcc, 0x2f618000, v30
	v_lshl_add_u64 v[34:35], v[30:31], 0, s[2:3]
	s_nop 0
	v_addc_co_u32_e32 v33, vcc, 0, v31, vcc
	global_load_dwordx4 v[46:49], v[32:33], off offset:256
	global_load_dwordx2 v[58:59], v[34:35], off offset:16
	v_add_co_u32_e32 v34, vcc, 0x32c18000, v30
	s_mov_b64 s[2:3], 0x32c18100
	s_nop 0
	v_addc_co_u32_e32 v35, vcc, 0, v31, vcc
	v_lshl_add_u64 v[36:37], v[30:31], 0, s[2:3]
	global_load_dwordx4 v[54:57], v[34:35], off offset:256
	global_load_dwordx2 v[60:61], v[36:37], off offset:16
	v_lshl_add_u64 v[34:35], v[26:27], 0, v[0:1]
	s_mov_b32 s1, 0x1afd9000
	v_add_co_u32_e32 v34, vcc, s1, v34
	s_mov_b32 s1, 0x800000
	s_nop 0
	v_addc_co_u32_e32 v35, vcc, 0, v35, vcc
	global_load_dwordx2 v[50:51], v[34:35], off offset:768
	global_load_dwordx2 v[100:101], v[34:35], off offset:776
	global_load_dwordx2 v[102:103], v[34:35], off offset:784
	v_add_co_u32_e32 v122, vcc, 0x36218000, v30
	s_nop 1
	v_addc_co_u32_e32 v123, vcc, 0, v31, vcc
	v_add_co_u32_e32 v124, vcc, 0x39818000, v30
	s_nop 1
	v_addc_co_u32_e32 v125, vcc, 0, v31, vcc
	v_add_co_u32_e32 v126, vcc, 0x28a18000, v30
	s_nop 1
	v_addc_co_u32_e32 v127, vcc, 0, v31, vcc
	global_load_dwordx2 v[104:105], v[122:123], off offset:256
	global_load_dwordx2 v[106:107], v[124:125], off offset:256
	global_load_dwordx2 v[108:109], v[126:127], off offset:256
	global_load_dwordx2 v[110:111], v[122:123], off offset:264
	global_load_dwordx2 v[112:113], v[124:125], off offset:264
	global_load_dwordx2 v[114:115], v[126:127], off offset:264
	global_load_dwordx2 v[116:117], v[122:123], off offset:272
	global_load_dwordx2 v[118:119], v[124:125], off offset:272
	global_load_dwordx2 v[120:121], v[126:127], off offset:272
	s_waitcnt vmcnt(15)
	v_lshlrev_b32_e32 v36, 16, v46
	v_and_b32_e32 v37, 0xffff0000, v46
	v_lshlrev_b32_e32 v38, 16, v47
	v_and_b32_e32 v39, 0xffff0000, v47
	v_lshlrev_b32_e32 v46, 16, v48
	v_and_b32_e32 v47, 0xffff0000, v48
	s_waitcnt vmcnt(13)
	v_lshlrev_b32_e32 v40, 16, v54
	v_and_b32_e32 v41, 0xffff0000, v54
	v_pk_add_f32 v[40:41], v[36:37], v[40:41]
	v_lshlrev_b32_e32 v42, 16, v55
	v_and_b32_e32 v43, 0xffff0000, v55
	v_pk_add_f32 v[38:39], v[38:39], v[42:43]
	v_pk_add_f32 v[42:43], v[40:41], v[40:41] op_sel:[0,1] op_sel_hi:[1,0]
	v_lshlrev_b32_e32 v44, 16, v56
	v_pk_add_f32 v[68:69], v[38:39], v[42:43]
	s_waitcnt vmcnt(11)
	v_lshlrev_b32_e32 v48, 16, v50
	v_mul_f32_e32 v48, 0xbfb8aa3b, v48
	v_exp_f32_e32 v52, v48
	v_and_b32_e32 v48, 0xffff0000, v50
	v_mul_f32_e32 v48, 0xbfb8aa3b, v48
	v_exp_f32_e32 v53, v48
	v_lshlrev_b32_e32 v48, 16, v51
	v_mul_f32_e32 v48, 0xbfb8aa3b, v48
	v_exp_f32_e32 v54, v48
	v_and_b32_e32 v48, 0xffff0000, v51
	v_mul_f32_e32 v48, 0xbfb8aa3b, v48
	v_pk_add_f32 v[36:37], v[52:53], 1.0 op_sel_hi:[1,0]
	v_exp_f32_e32 v55, v48
	v_div_scale_f32 v48, s[2:3], v37, v37, 1.0
	v_rcp_f32_e32 v50, v48
	v_lshlrev_b32_e32 v42, 16, v49
	v_lshlrev_b32_e32 v43, 16, v58
	v_pk_add_f32 v[54:55], v[54:55], 1.0 op_sel_hi:[1,0]
	v_fma_f32 v51, -v48, v50, 1.0
	v_fmac_f32_e32 v50, v51, v50
	v_div_scale_f32 v51, vcc, 1.0, v37, 1.0
	v_mul_f32_e32 v52, v51, v50
	v_fma_f32 v53, -v48, v52, v51
	v_fmac_f32_e32 v52, v53, v50
	v_fma_f32 v48, -v48, v52, v51
	v_div_fmas_f32 v48, v48, v50, v52
	v_div_fixup_f32 v37, v48, v37, 1.0
	v_div_scale_f32 v48, s[2:3], v36, v36, 1.0
	v_rcp_f32_e32 v50, v48
	v_and_b32_e32 v45, 0xffff0000, v56
	v_and_b32_e32 v56, 0xffff0000, v57
	v_pk_add_f32 v[44:45], v[46:47], v[44:45]
	v_fma_f32 v51, -v48, v50, 1.0
	v_fmac_f32_e32 v50, v51, v50
	v_div_scale_f32 v51, vcc, 1.0, v36, 1.0
	v_mul_f32_e32 v52, v51, v50
	v_fma_f32 v53, -v48, v52, v51
	v_fmac_f32_e32 v52, v53, v50
	v_fma_f32 v48, -v48, v52, v51
	v_div_fmas_f32 v48, v48, v50, v52
	v_lshlrev_b32_e32 v50, 16, v57
	v_lshlrev_b32_e32 v51, 16, v60
	v_div_fixup_f32 v36, v48, v36, 1.0
	v_pk_add_f32 v[42:43], v[42:43], v[50:51]
	v_and_b32_e32 v51, 0xffff0000, v58
	v_and_b32_e32 v48, 0xffff0000, v49
	v_lshlrev_b32_e32 v49, 16, v59
	v_and_b32_e32 v50, 0xffff0000, v59
	v_pk_add_f32 v[58:59], v[38:39], v[68:69] op_sel:[1,0] op_sel_hi:[0,1]
	v_mov_b32_e32 v59, v50
	v_div_scale_f32 v50, s[2:3], v55, v55, 1.0
	v_rcp_f32_e32 v52, v50
	v_lshlrev_b32_e32 v57, 16, v61
	v_pk_add_f32 v[48:49], v[48:49], v[56:57]
	v_and_b32_e32 v57, 0xffff0000, v61
	v_mov_b32_e32 v56, v1
	v_and_b32_e32 v53, 0xffff0000, v60
	v_pk_add_f32 v[60:61], v[58:59], v[56:57]
	v_fma_f32 v58, -v50, v52, 1.0
	v_fmac_f32_e32 v52, v58, v52
	v_div_scale_f32 v58, vcc, 1.0, v55, 1.0
	v_mul_f32_e32 v59, v58, v52
	v_fma_f32 v67, -v50, v59, v58
	v_fmac_f32_e32 v59, v67, v52
	v_fma_f32 v50, -v50, v59, v58
	v_div_fmas_f32 v50, v50, v52, v59
	v_div_fixup_f32 v55, v50, v55, 1.0
	v_div_scale_f32 v50, s[2:3], v54, v54, 1.0
	v_rcp_f32_e32 v52, v50
	v_mov_b32_e32 v57, v49
	v_mov_b32_e32 v56, v61
	v_fma_f32 v58, -v50, v52, 1.0
	v_fmac_f32_e32 v52, v58, v52
	v_div_scale_f32 v58, vcc, 1.0, v54, 1.0
	v_mul_f32_e32 v59, v58, v52
	v_fma_f32 v67, -v50, v59, v58
	v_fmac_f32_e32 v59, v67, v52
	v_fma_f32 v50, -v50, v59, v58
	v_div_fmas_f32 v50, v50, v52, v59
	v_div_fixup_f32 v54, v50, v54, 1.0
	v_mov_b32_e32 v50, v44
	v_mov_b32_e32 v52, v45
	v_pk_add_f32 v[46:47], v[50:51], v[52:53]
	v_mov_b32_e32 v59, v48
	v_pk_add_f32 v[50:51], v[42:43], v[46:47]
	v_mov_b32_e32 v58, v42
	v_pk_add_f32 v[48:49], v[48:49], v[50:51]
	s_nop 0
	v_pk_add_f32 v[48:49], v[60:61], v[48:49]
	s_nop 0
	v_add_f32_e32 v42, v48, v49
	s_nop 1
	v_mov_b32_dpp v46, v42 row_ror:8 row_mask:0xf bank_mask:0xf
	v_add_f32_e32 v42, v42, v46
	s_nop 1
	v_mov_b32_dpp v46, v42 row_shl:4 row_mask:0xf bank_mask:0x5
; DI unsigned pack2(float a, float b) { f32x2_t v = {a, b}; bf16x2_t r = __builtin_convertvector(v, bf16x2_t); return __builtin_bit_cast(unsigned, r); }
; DI float lo16(unsigned u) { return __uint_as_float(u << 16); }
; DI float hi16(unsigned u) { return __uint_as_float(u & 0xffff0000u); }
; DI float sigmoidf_(float x) { return 1.f / (1.f + __expf(-x)); }
; DI void post_scan(const PX& p, int l, int M, unsigned char* smem) {
;     ...
;       for (int o = 8; o >= 1; o >>= 1) s += __shfl_xor(s, o);
;       const float mu = s * (1.f / 192.f);
;       float q = 0.f;
; #pragma unroll
;       for (int i = 0; i < 12; i++) { x[i] -= mu; q += x[i] * x[i]; }
; #pragma unroll
;       for (int o = 8; o >= 1; o >>= 1) q += __shfl_xor(q, o);
;       const float rs = rsqrtf(q * (1.f / 192.f) + 1e-5f);
;       const uint2* og = (const uint2*)(Zml + (size_t)r * 3072 + 2304 + lane * 12);
;       const float4* gg = (const float4*)(ng + lane * 12);
; #pragma unroll
;       for (int i = 0; i < 3; i++) {
;         const uint2 o = og[i];
;         const float4 g4 = ngv[i];
;         uint2 w_;
;         w_.x = pack2(x[4 * i] * rs * g4.x * sigmoidf_(lo16(o.x)), x[4 * i + 1] * rs * g4.y * sigmoidf_(hi16(o.x)));
;         w_.y = pack2(x[4 * i + 2] * rs * g4.z * sigmoidf_(lo16(o.y)), x[4 * i + 3] * rs * g4.w * sigmoidf_(hi16(o.y)));
;         ((uint2*)(Hf + ro))[i] = w_;
;       }
	v_mov_b32_dpp v46, v42 row_shr:4 row_mask:0xf bank_mask:0xa
	v_add_f32_e32 v42, v42, v46
	s_nop 1
	v_mov_b32_dpp v46, v42 quad_perm:[2,3,0,1] row_mask:0xf bank_mask:0xf
	v_add_f32_e32 v42, v42, v46
	s_nop 1
	v_mov_b32_dpp v46, v42 quad_perm:[1,0,3,2] row_mask:0xf bank_mask:0xf
	v_add_f32_e32 v42, v42, v46
	v_mul_f32_e32 v42, 0x3baaaaab, v42
	v_pk_add_f32 v[48:49], v[40:41], v[42:43] op_sel_hi:[1,0] neg_lo:[0,1] neg_hi:[0,1]
	v_pk_add_f32 v[52:53], v[38:39], v[42:43] op_sel_hi:[1,0] neg_lo:[0,1] neg_hi:[0,1]
	v_pk_mul_f32 v[50:51], v[48:49], v[48:49]
	v_mov_b32_e32 v46, v43
	v_pk_mul_f32 v[60:61], v[52:53], v[52:53]
	v_pk_add_f32 v[40:41], v[46:47], v[42:43] op_sel_hi:[1,0] neg_lo:[0,1] neg_hi:[0,1]
	v_add_f32_e32 v46, v50, v51
	v_pk_add_f32 v[68:69], v[44:45], v[42:43] op_sel_hi:[1,0] neg_lo:[0,1] neg_hi:[0,1]
	v_add_f32_e32 v46, v60, v46
	v_pk_mul_f32 v[70:71], v[68:69], v[68:69]
	v_add_f32_e32 v46, v61, v46
	v_pk_add_f32 v[44:45], v[58:59], v[42:43] op_sel_hi:[1,0] neg_lo:[0,1] neg_hi:[0,1]
	v_add_f32_e32 v46, v70, v46
	v_pk_mul_f32 v[58:59], v[44:45], v[44:45]
	v_add_f32_e32 v46, v71, v46
	v_add_f32_e32 v46, v58, v46
	v_pk_add_f32 v[38:39], v[56:57], v[42:43] op_sel_hi:[1,0] neg_lo:[0,1] neg_hi:[0,1]
	v_pk_mul_f32 v[42:43], v[40:41], v[40:41]
	v_add_f32_e32 v46, v59, v46
	v_add_f32_e32 v42, v42, v46
	v_pk_mul_f32 v[56:57], v[38:39], v[38:39]
	v_add_f32_e32 v42, v43, v42
	v_add_f32_e32 v42, v57, v42
	v_add_f32_e32 v42, v56, v42
	s_nop 1
	v_mov_b32_dpp v43, v42 row_ror:8 row_mask:0xf bank_mask:0xf
	v_add_f32_e32 v42, v42, v43
	s_nop 1
	v_mov_b32_dpp v43, v42 row_shl:4 row_mask:0xf bank_mask:0x5
	v_mov_b32_dpp v43, v42 row_shr:4 row_mask:0xf bank_mask:0xa
	v_add_f32_e32 v42, v42, v43
	s_nop 1
	v_mov_b32_dpp v43, v42 quad_perm:[2,3,0,1] row_mask:0xf bank_mask:0xf
	v_add_f32_e32 v42, v42, v43
	s_nop 1
	v_mov_b32_dpp v43, v42 quad_perm:[1,0,3,2] row_mask:0xf bank_mask:0xf
	v_add_f32_e32 v42, v42, v43
	v_mov_b32_e32 v43, 0x3727c5ac
	v_fmamk_f32 v42, v42, 0x3baaaaab, v43
	v_cmp_gt_f32_e32 vcc, s1, v42
	v_mul_f32_e32 v43, 0x4b800000, v42
	s_mov_b32 s1, 0x36218000
	v_cndmask_b32_e32 v42, v42, v43, vcc
	v_rsq_f32_e32 v42, v42
	s_nop 0
	v_mul_f32_e32 v43, 0x45800000, v42
	v_cndmask_b32_e32 v42, v42, v43, vcc
	v_pk_mul_f32 v[46:47], v[48:49], v[42:43] op_sel_hi:[1,0]
	s_nop 0
	v_pk_mul_f32 v[46:47], v[6:7], v[46:47]
	s_nop 0
	v_pk_mul_f32 v[36:37], v[36:37], v[46:47]
	v_pk_mul_f32 v[46:47], v[52:53], v[42:43] op_sel_hi:[1,0]
	v_cvt_pk_bf16_f32 v36, v36, v37
	v_pk_mul_f32 v[46:47], v[8:9], v[46:47]
	s_nop 0
	v_pk_mul_f32 v[46:47], v[54:55], v[46:47]
	s_nop 0
	v_cvt_pk_bf16_f32 v37, v46, v47
	global_store_dwordx2 v[32:33], v[36:37], off offset:256
	s_waitcnt vmcnt(11)
	v_mov_b64_e32 v[36:37], v[100:101]
	v_lshlrev_b32_e32 v43, 16, v36
	v_and_b32_e32 v36, 0xffff0000, v36
	v_mul_f32_e32 v43, 0xbfb8aa3b, v43
	v_mul_f32_e32 v36, 0xbfb8aa3b, v36
	v_exp_f32_e32 v46, v43
	v_exp_f32_e32 v47, v36
	v_pk_mul_f32 v[48:49], v[68:69], v[42:43] op_sel_hi:[1,0]
	v_pk_add_f32 v[46:47], v[46:47], 1.0 op_sel_hi:[1,0]
	s_nop 0
	v_div_scale_f32 v36, s[2:3], v47, v47, 1.0
	v_rcp_f32_e32 v43, v36
	v_pk_mul_f32 v[48:49], v[2:3], v[48:49]
	v_fma_f32 v50, -v36, v43, 1.0
	v_fmac_f32_e32 v43, v50, v43
	v_div_scale_f32 v50, vcc, 1.0, v47, 1.0
	v_mul_f32_e32 v51, v50, v43
	v_fma_f32 v52, -v36, v51, v50
	v_fmac_f32_e32 v51, v52, v43
	v_fma_f32 v36, -v36, v51, v50
	v_div_fmas_f32 v36, v36, v43, v51
	v_div_fixup_f32 v47, v36, v47, 1.0
	v_div_scale_f32 v36, s[2:3], v46, v46, 1.0
	v_rcp_f32_e32 v43, v36
	s_nop 0
	v_fma_f32 v50, -v36, v43, 1.0
	v_fmac_f32_e32 v43, v50, v43
	v_div_scale_f32 v50, vcc, 1.0, v46, 1.0
	v_mul_f32_e32 v51, v50, v43
	v_fma_f32 v52, -v36, v51, v50
	v_fmac_f32_e32 v51, v52, v43
	v_fma_f32 v36, -v36, v51, v50
	v_div_fmas_f32 v36, v36, v43, v51
	v_div_fixup_f32 v46, v36, v46, 1.0
	v_lshlrev_b32_e32 v43, 16, v37
	v_and_b32_e32 v37, 0xffff0000, v37
	v_pk_mul_f32 v[46:47], v[46:47], v[48:49]
	v_mul_f32_e32 v43, 0xbfb8aa3b, v43
	v_mul_f32_e32 v37, 0xbfb8aa3b, v37
	v_cvt_pk_bf16_f32 v36, v46, v47
	v_exp_f32_e32 v46, v43
	v_exp_f32_e32 v47, v37
	v_pk_mul_f32 v[44:45], v[44:45], v[42:43] op_sel_hi:[1,0]
	v_pk_add_f32 v[46:47], v[46:47], 1.0 op_sel_hi:[1,0]
	s_nop 0
	v_div_scale_f32 v37, s[2:3], v47, v47, 1.0
	v_rcp_f32_e32 v43, v37
	v_pk_mul_f32 v[44:45], v[4:5], v[44:45]
	v_fma_f32 v48, -v37, v43, 1.0
	v_fmac_f32_e32 v43, v48, v43
	v_div_scale_f32 v48, vcc, 1.0, v47, 1.0
	v_mul_f32_e32 v49, v48, v43
	v_fma_f32 v50, -v37, v49, v48
	v_fmac_f32_e32 v49, v50, v43
	v_fma_f32 v37, -v37, v49, v48
	v_div_fmas_f32 v37, v37, v43, v49
	v_div_fixup_f32 v47, v37, v47, 1.0
	v_div_scale_f32 v37, s[2:3], v46, v46, 1.0
	v_rcp_f32_e32 v43, v37
	s_nop 0
	v_fma_f32 v48, -v37, v43, 1.0
	v_fmac_f32_e32 v43, v48, v43
	v_div_scale_f32 v48, vcc, 1.0, v46, 1.0
	v_mul_f32_e32 v49, v48, v43
	v_fma_f32 v50, -v37, v49, v48
	v_fmac_f32_e32 v49, v50, v43
	v_fma_f32 v37, -v37, v49, v48
	v_div_fmas_f32 v37, v37, v43, v49
	v_div_fixup_f32 v46, v37, v46, 1.0
	v_pk_mul_f32 v[44:45], v[46:47], v[44:45]
	v_pk_mul_f32 v[40:41], v[40:41], v[42:43] op_sel_hi:[1,0]
	v_cvt_pk_bf16_f32 v37, v44, v45
	global_store_dwordx2 v[32:33], v[36:37], off offset:264
	v_pk_mul_f32 v[40:41], v[10:11], v[40:41]
	s_waitcnt vmcnt(11)
; DI unsigned pack2(float a, float b) { f32x2_t v = {a, b}; bf16x2_t r = __builtin_convertvector(v, bf16x2_t); return __builtin_bit_cast(unsigned, r); }
; DI float lo16(unsigned u) { return __uint_as_float(u << 16); }
; DI float hi16(unsigned u) { return __uint_as_float(u & 0xffff0000u); }
; DI float sigmoidf_(float x) { return 1.f / (1.f + __expf(-x)); }
; DI void post_scan(const PX& p, int l, int M, unsigned char* smem) {
;     ...
;       const uint2* og = (const uint2*)(Zml + (size_t)r * 3072 + 2304 + lane * 12);
;       const float4* gg = (const float4*)(ng + lane * 12);
; #pragma unroll
;       for (int i = 0; i < 3; i++) {
;         const uint2 o = og[i];
;         const float4 g4 = ngv[i];
;         uint2 w_;
;         w_.x = pack2(x[4 * i] * rs * g4.x * sigmoidf_(lo16(o.x)), x[4 * i + 1] * rs * g4.y * sigmoidf_(hi16(o.x)));
;         w_.y = pack2(x[4 * i + 2] * rs * g4.z * sigmoidf_(lo16(o.y)), x[4 * i + 3] * rs * g4.w * sigmoidf_(hi16(o.y)));
;         ((uint2*)(Hf + ro))[i] = w_;
;       }
;     }
;     {
;       const uint2* yf = (const uint2*)(Yf + ro);
;       const uint2* yb = (const uint2*)(Yb + ro);
;       const uint2* zu = (const uint2*)(Zu + ro);
;       const float4* dd = (const float4*)(sd + lane * 12);
; #pragma unroll
;       for (int i = 0; i < 3; i++) {
;         const uint2 a = yf[i], bq = yb[i], u = zu[i];
;         const float4 d4 = sdv[i];
;         float y[4];
;         y[0] = lo16(a.x) + lo16(bq.x) + d4.x * lo16(u.x);
;         y[1] = hi16(a.x) + hi16(bq.x) + d4.y * hi16(u.x);
;         y[2] = lo16(a.y) + lo16(bq.y) + d4.z * lo16(u.y);
;         y[3] = hi16(a.y) + hi16(bq.y) + d4.w * hi16(u.y);
; #pragma unroll
;         for (int j = 0; j < 4; j++) {
;           const float uu = 0.7978845608028654f * (y[j] + 0.044715f * y[j] * y[j] * y[j]);
;           y[j] = 0.5f * y[j] * (1.f + tanhf(uu));
	v_mov_b64_e32 v[34:35], v[102:103]
	v_lshlrev_b32_e32 v36, 16, v34
	v_and_b32_e32 v34, 0xffff0000, v34
	v_mul_f32_e32 v36, 0xbfb8aa3b, v36
	v_mul_f32_e32 v34, 0xbfb8aa3b, v34
	v_exp_f32_e32 v36, v36
	v_exp_f32_e32 v37, v34
	s_nop 0
	v_pk_add_f32 v[36:37], v[36:37], 1.0 op_sel_hi:[1,0]
	s_nop 0
	v_div_scale_f32 v34, s[2:3], v37, v37, 1.0
	v_rcp_f32_e32 v43, v34
	s_nop 0
	v_fma_f32 v44, -v34, v43, 1.0
	v_fmac_f32_e32 v43, v44, v43
	v_div_scale_f32 v44, vcc, 1.0, v37, 1.0
	v_mul_f32_e32 v45, v44, v43
	v_fma_f32 v46, -v34, v45, v44
	v_fmac_f32_e32 v45, v46, v43
	v_fma_f32 v34, -v34, v45, v44
	v_div_fmas_f32 v34, v34, v43, v45
	v_div_fixup_f32 v37, v34, v37, 1.0
	v_div_scale_f32 v34, s[2:3], v36, v36, 1.0
	v_rcp_f32_e32 v43, v34
	s_nop 0
	v_fma_f32 v44, -v34, v43, 1.0
	v_fmac_f32_e32 v43, v44, v43
	v_div_scale_f32 v44, vcc, 1.0, v36, 1.0
	v_mul_f32_e32 v45, v44, v43
	v_fma_f32 v46, -v34, v45, v44
	v_fmac_f32_e32 v45, v46, v43
	v_fma_f32 v34, -v34, v45, v44
	v_div_fmas_f32 v34, v34, v43, v45
	v_div_fixup_f32 v36, v34, v36, 1.0
	v_pk_mul_f32 v[36:37], v[36:37], v[40:41]
	v_pk_mul_f32 v[38:39], v[38:39], v[42:43] op_sel_hi:[1,0]
	v_cvt_pk_bf16_f32 v34, v36, v37
	v_lshlrev_b32_e32 v36, 16, v35
	v_and_b32_e32 v35, 0xffff0000, v35
	v_mul_f32_e32 v36, 0xbfb8aa3b, v36
	v_mul_f32_e32 v35, 0xbfb8aa3b, v35
	v_exp_f32_e32 v36, v36
	v_exp_f32_e32 v37, v35
	v_pk_mul_f32 v[38:39], v[12:13], v[38:39] op_sel:[0,1] op_sel_hi:[1,0]
	v_pk_add_f32 v[36:37], v[36:37], 1.0 op_sel_hi:[1,0]
	s_nop 0
	v_div_scale_f32 v35, s[2:3], v37, v37, 1.0
	v_rcp_f32_e32 v40, v35
	s_nop 0
	v_fma_f32 v41, -v35, v40, 1.0
	v_fmac_f32_e32 v40, v41, v40
	v_div_scale_f32 v41, vcc, 1.0, v37, 1.0
	v_mul_f32_e32 v42, v41, v40
	v_fma_f32 v43, -v35, v42, v41
	v_fmac_f32_e32 v42, v43, v40
	v_fma_f32 v35, -v35, v42, v41
	v_div_fmas_f32 v35, v35, v40, v42
	v_div_fixup_f32 v37, v35, v37, 1.0
	v_div_scale_f32 v35, s[2:3], v36, v36, 1.0
	v_rcp_f32_e32 v40, v35
	s_nop 0
	v_fma_f32 v41, -v35, v40, 1.0
	v_fmac_f32_e32 v40, v41, v40
	v_div_scale_f32 v41, vcc, 1.0, v36, 1.0
	v_mul_f32_e32 v42, v41, v40
	v_fma_f32 v43, -v35, v42, v41
	v_fmac_f32_e32 v42, v43, v40
	v_fma_f32 v35, -v35, v42, v41
	v_div_fmas_f32 v35, v35, v40, v42
	v_div_fixup_f32 v36, v35, v36, 1.0
	v_pk_mul_f32 v[36:37], v[36:37], v[38:39]
	s_nop 0
	v_cvt_pk_bf16_f32 v35, v36, v37
	global_store_dwordx2 v[32:33], v[34:35], off offset:272
	v_add_co_u32_e32 v32, vcc, s1, v30
	s_mov_b32 s1, 0x39818000
	s_nop 0
	v_addc_co_u32_e32 v33, vcc, 0, v31, vcc
	v_add_co_u32_e32 v34, vcc, s1, v30
	s_mov_b32 s1, 0x28a18000
	s_nop 0
	v_addc_co_u32_e32 v35, vcc, 0, v31, vcc
	v_add_co_u32_e32 v36, vcc, s1, v30
	v_addc_co_u32_e32 v37, vcc, 0, v31, vcc
	s_mov_b32 s1, 0x3f200000
	s_waitcnt vmcnt(11)
	v_mov_b64_e32 v[38:39], v[104:105]
	v_lshlrev_b32_e32 v44, 16, v38
	s_waitcnt vmcnt(10)
	v_mov_b64_e32 v[40:41], v[106:107]
	v_lshlrev_b32_e32 v45, 16, v40
	v_add_f32_e32 v44, v45, v44
	s_waitcnt vmcnt(9)
	v_mov_b64_e32 v[42:43], v[108:109]
	v_lshlrev_b32_e32 v45, 16, v42
	v_fmac_f32_e32 v44, v14, v45
	v_mul_f32_e32 v45, 0x3d372713, v44
	v_mul_f32_e32 v45, v44, v45
	v_fma_f32 v45, v44, v45, v44
	v_mul_f32_e32 v45, 0x3f4c422a, v45
	v_cmp_nlt_f32_e64 s[2:3], |v45|, s1
	s_and_saveexec_b64 s[12:13], s[2:3]
	s_xor_b64 s[12:13], exec, s[12:13]
	s_cbranch_execz .LBB0_373
	v_add_f32_e64 v46, |v45|, |v45|
	v_mul_f32_e32 v47, 0x3fb8aa3b, v46
	v_rndne_f32_e32 v48, v47
	s_mov_b32 s2, 0x3fb8aa3b
	v_sub_f32_e32 v49, v47, v48
	v_fma_f32 v47, v46, s2, -v47
	v_fmac_f32_e32 v47, 0x32a5705f, v46
	v_add_f32_e32 v47, v49, v47
	v_cvt_i32_f32_e32 v48, v48
	v_exp_f32_e32 v47, v47
	s_mov_b32 s2, 0xc2ce8ed0
	v_cmp_ngt_f32_e32 vcc, s2, v46
	s_mov_b32 s2, 0x42b17218
	v_ldexp_f32 v47, v47, v48
	v_cndmask_b32_e32 v47, 0, v47, vcc
	v_cmp_nlt_f32_e32 vcc, s2, v46
	s_nop 1
	v_cndmask_b32_e32 v46, v212, v47, vcc
	v_add_f32_e32 v46, 1.0, v46
	v_rcp_f32_e32 v46, v46
	s_nop 0
	v_fma_f32 v46, v46, -2.0, 1.0
